# attention: packed P used without the cross-half permlane32_swap (V tile rows stored in the matching order)
# speedup vs baseline: 1.0055x; 1.0055x over previous
; __device__ __forceinline__ int v_st(int k, int c) { const int kk = (k & ~0xC) | ((k & 4) << 1) | ((k & 8) >> 1); return ((kk >> 3) * 4 + (c >> 5)) * 512 + ((kk & 7) * 32 + (c & 31)) * 2; }
; __device__ __forceinline__ int v_rd_base(int lane) { return ((lane & 3) << 3) | (((lane >> 2) & 3) << 6) | (((lane >> 4) & 1) << 5) | (((lane >> 5) & 1) << 8); }
; #define SLOAD(i, k0) do { const char* vt_ = (const char*)Vh + (size_t)(k0) * 256; const char* kt_ = (const char*)Kh + (size_t)(k0) * 128; \
;     sr_[i].vs0 = *reinterpret_cast<const bf16x8*>(vt_ + voff0); sr_[i].vs1 = *reinterpret_cast<const bf16x8*>(vt_ + 32 * 256 + voff0); \
;     sr_[i].ks0 = *reinterpret_cast<const bf16x8*>(kt_ + koff0); } while (0)
; #define SWRITE(b, i) do { *(bf16x8*)(V_lds + (b) * SHM_V + vst0) = sr_[i].vs0; *(bf16x8*)(V_lds + (b) * SHM_V + vst1) = sr_[i].vs1; \
;     *(bf16x8*)(K_lds + (b) * SHM_K + kst) = sr_[i].ks0; } while (0)
; __device__ __forceinline__ void attn_unit(const bf16* __restrict__ Qb, const bf16* __restrict__ Kh, const bf16* __restrict__ Vh, bf16* __restrict__ Ob, int seq, char* lds) {
;     int tid = threadIdx.x; asm volatile("" : "+v"(tid));
;     const int wid = tid >> 6, lane = tid & 63, r32 = lane & 31, hi = lane >> 5;
;     char* V_lds = lds; char* K_lds = lds + 2 * SHM_V;
;     float* wsf = (float*)(lds + 2 * SHM_V + 2 * SHM_K) + wid * 64;
;     float l_reg = 0; f32x16 o[4] = {}; bf16x8 qr[4];
;     const bf16* Qw = Qb + (long)(wid * QBLK + r32) * 64 + hi * 8;
; #pragma unroll
;     for (int d0 = 0; d0 < 4; ++d0) qr[d0] = *reinterpret_cast<const bf16x8*>(Qw + d0 * 16);
;     const int sr = tid >> 4, sc = (tid & 15) * 8, vst0 = v_st(sr, sc), vst1 = v_st(32 + sr, sc);
;     const int kr = tid >> 3, kc = (tid & 7) * 8, kst = KSWZ64(kr, kc * 2);
;     const int vb0 = (int)(uintptr_t)V_lds + v_rd_base(lane);
;     struct { bf16x8 vs0, vs1, ks0; } sr_[1];
;     const unsigned voff0 = (unsigned)((sr * 128 + sc) * 2), koff0 = (unsigned)((kr * 64 + kc) * 2);
;     ...
;     f32x16 pA0, pA1, pB0, pB1; bf16x8 pa0, pa1, pa2, pa3; const int NT = seq / KVBLK;
;     constexpr int SE = 0, SO = 0;
;     SLOAD(SE, 0); asm volatile("s_waitcnt vmcnt(0)" ::: "memory"); SWRITE(0, SE); __syncthreads();
;     qkt(pA0, pA1, K_lds, qr, r32, hi); softHalf(pA0, l_reg, pa0, pa1);
.LBB0_530:
	s_and_b32 s6, s49, 7
	s_and_b32 s58, s50, 7
	s_lshl_b32 s51, s6, 3
	s_lshl_b32 s52, s6, 2
	s_ashr_i32 s53, s50, 6
	s_lshl_b32 s6, s58, 3
	s_add_i32 s10, s6, s53
	s_ashr_i32 s11, s10, 31
	s_lshl_b64 s[6:7], s[10:11], 11
	s_lshl_b32 s11, s50, 5
	s_and_b32 s11, s11, 0x700
	s_or_b32 s6, s6, s11
	s_lshl_b64 s[12:13], s[6:7], 7
	s_add_u32 s12, s3, s12
	s_addc_u32 s13, s14, s13
	s_mul_hi_i32 s11, s10, 0x48000
	s_mul_i32 s10, s10, 0x48000
	s_add_u32 s10, s15, s10
	s_addc_u32 s11, s16, s11
	s_lshl_b32 s59, s58, 2
	s_ashr_i32 s58, s50, 7
	v_mov_b32_e32 v143, v0
	s_add_i32 s59, s59, s58
	s_mul_hi_i32 s65, s59, 0x90000
	v_lshlrev_b32_e32 v17, 3, v143
	s_mul_i32 s59, s59, 0x90000
	v_and_b32_e32 v2, 0x78, v17
	s_add_u32 s64, s17, s59
	v_ashrrev_i32_e32 v16, 4, v143
	v_lshlrev_b32_e32 v18, 1, v2
	s_addc_u32 s65, s19, s65
	v_lshl_or_b32 v42, v16, 8, v18
	v_mov_b32_e32 v43, v138
	v_lshl_add_u64 v[38:39], s[64:65], 0, v[42:43]
	v_add_co_u32_e32 v6, vcc, s23, v38
	v_lshlrev_b32_e32 v140, 4, v143
	s_nop 0
	v_addc_co_u32_e32 v7, vcc, 0, v39, vcc
	global_load_dwordx4 v[2:5], v42, s[64:65]
	s_nop 0
	global_load_dwordx4 v[6:9], v[6:7], off
	s_nop 0
	global_load_dwordx4 v[10:13], v140, s[10:11]
	v_ashrrev_i32_e32 v155, 6, v143
	v_and_b32_e32 v153, 31, v143
	v_lshlrev_b32_e32 v142, 5, v155
	v_or_b32_e32 v14, v142, v153
	v_ashrrev_i32_e32 v15, 31, v14
	v_bfe_u32 v154, v143, 5, 1
	v_lshlrev_b64 v[14:15], 7, v[14:15]
	v_lshl_add_u64 v[14:15], s[12:13], 0, v[14:15]
	v_lshlrev_b32_e32 v144, 4, v154
	v_mov_b32_e32 v145, v138
	v_lshl_add_u64 v[14:15], v[14:15], 0, v[144:145]
	global_load_dwordx4 v[126:129], v[14:15], off
	global_load_dwordx4 v[122:125], v[14:15], off offset:32
	global_load_dwordx4 v[118:121], v[14:15], off offset:64
	global_load_dwordx4 v[114:117], v[14:15], off offset:96
	v_and_b32_e32 v14, 0xfffff8, v16
	v_lshlrev_b32_e32 v15, 1, v16
	v_lshrrev_b32_e32 v19, 1, v16
	v_and_b32_e32 v21, 3, v16
	v_add_u32_e32 v16, 32, v16
	v_bfe_u32 v20, v17, 5, 2
	v_and_b32_e32 v31, 0x70, v17
	v_and_or_b32 v14, v15, 0, v14
	v_and_b32_e32 v17, 0xfffff8, v16
	v_lshlrev_b32_e32 v16, 1, v16
	v_lshrrev_b32_e32 v14, 1, v14
	v_and_or_b32 v16, v16, 0, v17
	v_bfe_u32 v15, v15, 1, 3
	v_or_b32_e32 v14, v14, v20
	v_lshrrev_b32_e32 v16, 1, v16
	v_lshlrev_b32_e32 v30, 7, v153
	v_lshlrev_b32_e32 v15, 6, v15
	v_and_b32_e32 v18, 48, v18
	v_lshlrev_b32_e32 v14, 9, v14
	v_or_b32_e32 v16, v16, v20
	v_and_b32_e32 v22, 0xffffff80, v140
	v_xor_b32_e32 v23, v140, v143
	v_bitop3_b32 v21, v144, v30, v31 bitop3:0xde
	v_or3_b32 v14, v14, v15, v18
	v_lshlrev_b32_e32 v16, 9, v16
	v_and_or_b32 v19, v23, s22, v22
	v_add_u32_e32 v157, 0, v21
	v_or3_b32 v15, v16, v15, v18
	v_add_u32_e32 v160, 0, v14
	v_add_u32_e32 v158, 0, v19
	v_add_u32_e32 v161, 0, v15
	s_waitcnt vmcnt(0)
	v_or_b32_e32 v26, 64, v144
	v_bitop3_b32 v26, v26, v30, v31 bitop3:0xde
	v_add_u32_e32 v162, 0, v26
	v_or_b32_e32 v32, 0x60, v144
	v_mov_b32_e32 v141, v138
	v_lshl_add_u64 v[40:41], s[10:11], 0, v[140:141]
	v_and_b32_e32 v145, 63, v143
	s_cmp_lg_u32 0, -1
	s_cselect_b32 s11, 0, 0
	s_add_i32 s53, s53, s51
	v_mad_i64_i32 v[146:147], s[12:13], s53, v1, v[140:141]
	s_add_i32 s58, s58, s52
	s_waitcnt vmcnt(6)
	ds_write_b128 v160, v[2:5]
	s_waitcnt vmcnt(5)
	ds_write_b128 v161, v[6:9]
	s_waitcnt vmcnt(4)
	ds_write_b128 v158, v[10:13] offset:32768
	s_waitcnt lgkmcnt(0)
	s_barrier
	ds_read_b128 v[2:5], v157 offset:32768
	ds_read_b128 v[18:21], v157 offset:36864
	v_or_b32_e32 v6, 32, v144
	v_bitop3_b32 v6, v6, v30, v31 bitop3:0xde
	v_add_u32_e32 v159, 0, v6
	ds_read_b128 v[22:25], v159 offset:32768
	ds_read_b128 v[26:29], v159 offset:36864
	s_waitcnt vmcnt(3) lgkmcnt(3)
	v_mfma_f32_32x32x16_bf16 v[2:17], v[2:5], v[126:129], 0
	v_bitop3_b32 v30, v32, v30, v31 bitop3:0xde
	v_add_u32_e32 v163, 0, v30
	ds_read_b128 v[30:33], v162 offset:36864
	ds_read_b128 v[34:37], v163 offset:36864
	s_mov_b32 s10, -1
	v_mad_i64_i32 v[148:149], s[12:13], s58, v152, v[42:43]
	s_waitcnt vmcnt(2) lgkmcnt(3)
	v_mfma_f32_32x32x16_bf16 v[2:17], v[22:25], v[122:125], v[2:17]
	ds_read_b128 v[22:25], v162 offset:32768
	v_mov_b32_e32 v42, v138
	v_mov_b32_e32 v57, v138
	v_mov_b32_e32 v58, v138
	v_mov_b32_e32 v59, v138
	v_mov_b32_e32 v60, v138
	v_mov_b32_e32 v61, v138
	s_waitcnt vmcnt(1) lgkmcnt(0)
	v_mfma_f32_32x32x16_bf16 v[2:17], v[22:25], v[118:121], v[2:17]
	ds_read_b128 v[22:25], v163 offset:32768
	v_mov_b32_e32 v62, v138
	v_mov_b32_e32 v63, v138
	v_mov_b32_e32 v64, v138
	v_mov_b32_e32 v65, v138
	s_waitcnt vmcnt(0) lgkmcnt(0)
	v_mfma_f32_32x32x16_bf16 v[2:17], v[22:25], v[114:117], v[2:17]
	v_mfma_f32_32x32x16_bf16 v[66:81], v[18:21], v[126:129], 0
	s_nop 10
	v_exp_f32_e32 v44, v2
	v_add_co_u32_e32 v2, vcc, s34, v38
	v_exp_f32_e32 v45, v3
	s_nop 0
	v_addc_co_u32_e32 v3, vcc, 0, v39, vcc
	v_exp_f32_e32 v46, v4
	v_add_co_u32_e32 v4, vcc, s35, v38
	v_exp_f32_e32 v47, v5
	s_nop 0
	v_addc_co_u32_e32 v5, vcc, 0, v39, vcc
	v_exp_f32_e32 v48, v6
	v_exp_f32_e32 v49, v7
	v_exp_f32_e32 v50, v8
	v_exp_f32_e32 v51, v9
	v_exp_f32_e32 v52, v10
	v_exp_f32_e32 v11, v11
	v_exp_f32_e32 v53, v12
	v_exp_f32_e32 v54, v13
	v_exp_f32_e32 v55, v14
	v_exp_f32_e32 v56, v15
	v_exp_f32_e32 v16, v16
	v_exp_f32_e32 v17, v17
	v_cvt_pk_bf16_f32 v134, v44, v45
	v_cvt_pk_bf16_f32 v135, v46, v47
	v_cvt_pk_bf16_f32 v136, v48, v49
	v_cvt_pk_bf16_f32 v137, v50, v51
	v_cvt_pk_bf16_f32 v130, v52, v11
	v_cvt_pk_bf16_f32 v131, v53, v54
	v_cvt_pk_bf16_f32 v132, v55, v56
	v_cvt_pk_bf16_f32 v133, v16, v17
	global_load_dwordx4 v[12:15], v[2:3], off
	global_load_dwordx4 v[22:25], v[4:5], off
	v_add_co_u32_e32 v2, vcc, s23, v40
	v_mfma_f32_32x32x16_bf16 v[66:81], v[26:29], v[122:125], v[66:81]
	s_nop 0
	v_addc_co_u32_e32 v3, vcc, 0, v41, vcc
	global_load_dwordx4 v[38:41], v[2:3], off
	v_lshlrev_b32_e32 v18, 1, v143
	v_lshlrev_b32_e32 v19, 3, v145
	v_and_b32_e32 v20, 0xc0, v140
	v_and_b32_e32 v18, 32, v18
	v_and_or_b32 v20, v19, 24, v20
	v_and_b32_e32 v19, 0x100, v19
	v_or3_b32 v18, v20, v18, v19
	v_add_u32_e32 v156, s11, v18
	s_addk_i32 s11, 0x4000
	v_add_u32_e32 v141, s11, v18
	v_add_f32_e32 v18, 0, v44
	v_mfma_f32_32x32x16_bf16 v[66:81], v[30:33], v[118:121], v[66:81]
	v_add_f32_e32 v18, v45, v18
	v_add_f32_e32 v18, v46, v18
	v_add_f32_e32 v18, v47, v18
	v_add_f32_e32 v18, v48, v18
	v_add_f32_e32 v18, v49, v18
	v_add_f32_e32 v18, v50, v18
	v_add_f32_e32 v18, v51, v18
	v_add_f32_e32 v18, v52, v18
	v_mfma_f32_32x32x16_bf16 v[66:81], v[34:37], v[114:117], v[66:81]
	v_add_f32_e32 v11, v11, v18
	v_add_f32_e32 v11, v53, v11
	v_add_f32_e32 v11, v54, v11
	v_add_f32_e32 v11, v55, v11
	v_add_f32_e32 v11, v56, v11
	s_waitcnt vmcnt(0)
; #define SBAR() __builtin_amdgcn_sched_barrier(0)
; #define SLOAD(i, k0) do { const char* vt_ = (const char*)Vh + (size_t)(k0) * 256; const char* kt_ = (const char*)Kh + (size_t)(k0) * 128; \
;     sr_[i].vs0 = *reinterpret_cast<const bf16x8*>(vt_ + voff0); sr_[i].vs1 = *reinterpret_cast<const bf16x8*>(vt_ + 32 * 256 + voff0); \
;     sr_[i].ks0 = *reinterpret_cast<const bf16x8*>(kt_ + koff0); } while (0)
; #define SWRITE(b, i) do { *(bf16x8*)(V_lds + (b) * SHM_V + vst0) = sr_[i].vs0; *(bf16x8*)(V_lds + (b) * SHM_V + vst1) = sr_[i].vs1; \
;     *(bf16x8*)(K_lds + (b) * SHM_K + kst) = sr_[i].ks0; } while (0)
; #define SWAIT() asm volatile("s_waitcnt vmcnt(0)" ::: "memory")
; #define SBAR() __builtin_amdgcn_sched_barrier(0)
; __device__ __forceinline__ void attn_unit(const bf16* __restrict__ Qb, const bf16* __restrict__ Kh, const bf16* __restrict__ Vh, bf16* __restrict__ Ob, int seq, char* lds) {
;     ...
;     qkt(pA0, pA1, K_lds, qr, r32, hi); softHalf(pA0, l_reg, pa0, pa1);
;     SLOAD(SO, KVBLK);
;     SWAIT(); SWRITE(1, SO); __syncthreads();
;     for (int j = 1; j + 1 < NT; j += 2) {
;         SBAR(); qkt(pB0, pB1, K_lds + SHM_K, qr, r32, hi); pv_ks<0>(o, vb0, pa0); SBAR();
;         softHalf(pA1, l_reg, pa2, pa3); SBAR();
;         SLOAD(SO, (j + 1) * KVBLK); SBAR();
;         pv_ks<1>(o, vb0, pa1); pv_ks<2>(o, vb0, pa2); pv_ks<3>(o, vb0, pa3); SBAR();
	v_add_f32_e32 v11, v16, v11
	v_add_f32_e32 v11, v17, v11
	v_mov_b32_e32 v2, v138
	v_mov_b32_e32 v3, v138
	v_mov_b32_e32 v4, v138
	v_mov_b32_e32 v5, v138
	v_mov_b32_e32 v6, v138
	v_mov_b32_e32 v7, v138
	v_mov_b32_e32 v8, v138
	v_mov_b32_e32 v9, v138
	v_mov_b32_e32 v10, v138
	v_add_f32_e32 v139, 0, v11
	s_waitcnt vmcnt(2)
	ds_write_b128 v160, v[12:15] offset:16384
	s_waitcnt vmcnt(1)
	ds_write_b128 v161, v[22:25] offset:16384
	s_waitcnt vmcnt(0)
	ds_write_b128 v158, v[38:41] offset:40960
	v_mov_b32_e32 v11, v138
	v_mov_b32_e32 v12, v138
	v_mov_b32_e32 v13, v138
	v_mov_b32_e32 v14, v138
	v_mov_b32_e32 v15, v138
	v_mov_b32_e32 v16, v138
	v_mov_b32_e32 v17, v138
	v_mov_b32_e32 v18, v138
	v_mov_b32_e32 v19, v138
	v_mov_b32_e32 v20, v138
	v_mov_b32_e32 v21, v138
	v_mov_b32_e32 v22, v138
	v_mov_b32_e32 v23, v138
	v_mov_b32_e32 v24, v138
	v_mov_b32_e32 v25, v138
	v_mov_b32_e32 v26, v138
	v_mov_b32_e32 v27, v138
	v_mov_b32_e32 v28, v138
	v_mov_b32_e32 v29, v138
	v_mov_b32_e32 v30, v138
	v_mov_b32_e32 v31, v138
	v_mov_b32_e32 v32, v138
	v_mov_b32_e32 v33, v138
	v_mov_b32_e32 v34, v138
	v_mov_b32_e32 v35, v138
	v_mov_b32_e32 v36, v138
	v_mov_b32_e32 v37, v138
	v_mov_b32_e32 v38, v138
	v_mov_b32_e32 v39, v138
	v_mov_b32_e32 v40, v138
	v_mov_b32_e32 v41, v138
	v_mov_b32_e32 v44, v138
	v_mov_b32_e32 v45, v138
	v_mov_b32_e32 v46, v138
	v_mov_b32_e32 v47, v138
	v_mov_b32_e32 v48, v138
	v_mov_b32_e32 v49, v138
	v_mov_b32_e32 v50, v138
	v_mov_b32_e32 v51, v138
	v_mov_b32_e32 v52, v138
	v_mov_b32_e32 v53, v138
	v_mov_b32_e32 v54, v138
	v_mov_b32_e32 v55, v138
	v_mov_b32_e32 v56, v138
	s_waitcnt lgkmcnt(0)
	s_barrier
.LBB0_531:
	ds_read_b128 v[82:85], v157 offset:40960
	ds_read_b128 v[86:89], v157 offset:45056
	ds_read_b128 v[164:167], v159 offset:40960
	ds_read_b128 v[168:171], v159 offset:45056
	ds_read_b128 v[188:191], v162 offset:40960
	ds_read_b128 v[230:233], v162 offset:45056
	ds_read_b128 v[234:237], v163 offset:40960
	ds_read_b128 v[242:245], v163 offset:45056
	v_exp_f32_e32 v66, v66
	v_exp_f32_e32 v67, v67
	v_exp_f32_e32 v68, v68
	v_exp_f32_e32 v69, v69
	s_waitcnt lgkmcnt(7)
	v_mfma_f32_32x32x16_bf16 v[98:113], v[82:85], v[126:129], 0
	v_exp_f32_e32 v70, v70
	v_add_f32_e32 v179, 0, v66
	s_waitcnt lgkmcnt(6)
	v_mfma_f32_32x32x16_bf16 v[82:97], v[86:89], v[126:129], 0
	v_exp_f32_e32 v71, v71
	v_add_f32_e32 v179, v67, v179
	v_exp_f32_e32 v72, v72
	v_add_f32_e32 v179, v68, v179
	s_waitcnt lgkmcnt(5)
	v_mfma_f32_32x32x16_bf16 v[98:113], v[164:167], v[122:125], v[98:113]
	v_exp_f32_e32 v73, v73
	v_add_f32_e32 v179, v69, v179
	v_exp_f32_e32 v74, v74
	s_waitcnt lgkmcnt(4)
	v_mfma_f32_32x32x16_bf16 v[82:97], v[168:171], v[122:125], v[82:97]
	ds_read_b64_tr_b16 v[172:173], v156 offset:0
	ds_read_b64_tr_b16 v[174:175], v156 offset:0x800
	ds_read_b64_tr_b16 v[164:165], v156 offset:0x200
	ds_read_b64_tr_b16 v[166:167], v156 offset:0xa00
	ds_read_b64_tr_b16 v[180:181], v156 offset:0x400
	ds_read_b64_tr_b16 v[182:183], v156 offset:0xc00
	ds_read_b64_tr_b16 v[184:185], v156 offset:0x600
	ds_read_b64_tr_b16 v[186:187], v156 offset:0xe00
	v_add_f32_e32 v179, v70, v179
	v_exp_f32_e32 v75, v75
	v_add_f32_e32 v179, v71, v179
	s_waitcnt lgkmcnt(11)
	v_mfma_f32_32x32x16_bf16 v[98:113], v[188:191], v[118:121], v[98:113]
	v_exp_f32_e32 v76, v76
	v_add_f32_e32 v179, v72, v179
	v_exp_f32_e32 v77, v77
	s_waitcnt lgkmcnt(10)
	v_mfma_f32_32x32x16_bf16 v[82:97], v[230:233], v[118:121], v[82:97]
	v_add_f32_e32 v179, v73, v179
	v_exp_f32_e32 v78, v78
	v_add_f32_e32 v179, v74, v179
	s_waitcnt lgkmcnt(9)
	v_mfma_f32_32x32x16_bf16 v[98:113], v[234:237], v[114:117], v[98:113]
	v_exp_f32_e32 v79, v79
	v_add_f32_e32 v179, v75, v179
	v_exp_f32_e32 v80, v80
	s_waitcnt lgkmcnt(8)
	v_mfma_f32_32x32x16_bf16 v[82:97], v[242:245], v[114:117], v[82:97]
	v_add_f32_e32 v179, v76, v179
	v_exp_f32_e32 v81, v81
	v_add_f32_e32 v179, v77, v179
	v_add_f32_e32 v179, v78, v179
	s_waitcnt lgkmcnt(6)
	v_mfma_f32_32x32x16_bf16 v[2:17], v[134:137], v[172:175], v[2:17]
	ds_read_b64_tr_b16 v[188:189], v156 offset:0x1000
	ds_read_b64_tr_b16 v[190:191], v156 offset:0x1800
	ds_read_b64_tr_b16 v[230:231], v156 offset:0x1200
	ds_read_b64_tr_b16 v[232:233], v156 offset:0x1a00
	ds_read_b64_tr_b16 v[234:235], v156 offset:0x1400
	ds_read_b64_tr_b16 v[236:237], v156 offset:0x1c00
	ds_read_b64_tr_b16 v[242:243], v156 offset:0x1600
	ds_read_b64_tr_b16 v[244:245], v156 offset:0x1e00
	v_add_f32_e32 v179, v79, v179
	v_add_f32_e32 v179, v80, v179
	v_add_f32_e32 v179, v81, v179
	v_cvt_pk_bf16_f32 v66, v66, v67
	s_waitcnt lgkmcnt(12)
	v_mfma_f32_32x32x16_bf16 v[18:33], v[134:137], v[164:167], v[18:33]
	v_cvt_pk_bf16_f32 v67, v68, v69
	v_cvt_pk_bf16_f32 v68, v70, v71
	v_cvt_pk_bf16_f32 v69, v72, v73
	v_cvt_pk_bf16_f32 v70, v74, v75
	s_waitcnt lgkmcnt(10)
	v_mfma_f32_32x32x16_bf16 v[34:49], v[134:137], v[180:183], v[34:49]
	v_cvt_pk_bf16_f32 v71, v76, v77
	v_cvt_pk_bf16_f32 v72, v78, v79
	v_cvt_pk_bf16_f32 v73, v80, v81
	v_add_f32_e32 v221, v139, v179
	s_waitcnt lgkmcnt(8)
	v_mfma_f32_32x32x16_bf16 v[50:65], v[134:137], v[184:187], v[50:65]
	v_lshl_add_u64 v[136:137], s[30:31], 0, v[148:149]
	v_add_co_u32_e32 v74, vcc, s40, v136
	v_lshl_add_u64 v[150:151], s[30:31], 0, v[146:147]
	s_nop 0
	v_addc_co_u32_e32 v75, vcc, 0, v137, vcc
	v_add_co_u32_e32 v78, vcc, s41, v136
	s_nop 1
	v_addc_co_u32_e32 v79, vcc, 0, v137, vcc
	v_add_co_u32_e32 v164, vcc, s42, v150
	s_waitcnt lgkmcnt(6)
; #define SBAR() __builtin_amdgcn_sched_barrier(0)
; #define SLOAD(i, k0) do { const char* vt_ = (const char*)Vh + (size_t)(k0) * 256; const char* kt_ = (const char*)Kh + (size_t)(k0) * 128; \
;     sr_[i].vs0 = *reinterpret_cast<const bf16x8*>(vt_ + voff0); sr_[i].vs1 = *reinterpret_cast<const bf16x8*>(vt_ + 32 * 256 + voff0); \
;     sr_[i].ks0 = *reinterpret_cast<const bf16x8*>(kt_ + koff0); } while (0)
; #define SWRITE(b, i) do { *(bf16x8*)(V_lds + (b) * SHM_V + vst0) = sr_[i].vs0; *(bf16x8*)(V_lds + (b) * SHM_V + vst1) = sr_[i].vs1; \
;     *(bf16x8*)(K_lds + (b) * SHM_K + kst) = sr_[i].ks0; } while (0)
; #define SWAIT() asm volatile("s_waitcnt vmcnt(0)" ::: "memory")
; #define SBAR() __builtin_amdgcn_sched_barrier(0)
; __device__ __forceinline__ void attn_unit(const bf16* __restrict__ Qb, const bf16* __restrict__ Kh, const bf16* __restrict__ Vh, bf16* __restrict__ Ob, int seq, char* lds) {
;     ...
;         SLOAD(SO, (j + 1) * KVBLK); SBAR();
;         pv_ks<1>(o, vb0, pa1); pv_ks<2>(o, vb0, pa2); pv_ks<3>(o, vb0, pa3); SBAR();
;         softHalf(pB0, l_reg, pa0, pa1); SBAR();
;         __syncthreads(); SWAIT(); SWRITE(0, SE);
;         __syncthreads();
;         SBAR(); qkt(pA0, pA1, K_lds, qr, r32, hi); pv_ks<0>(o, vb0 + SHM_V, pa0); SBAR();
;         softHalf(pB1, l_reg, pa2, pa3); SBAR();
;         SLOAD(SE, (j + 2) * KVBLK); SBAR();
;         pv_ks<1>(o, vb0 + SHM_V, pa1); pv_ks<2>(o, vb0 + SHM_V, pa2); pv_ks<3>(o, vb0 + SHM_V, pa3); SBAR();
	v_mfma_f32_32x32x16_bf16 v[2:17], v[130:133], v[188:191], v[2:17]
	ds_read_b64_tr_b16 v[168:169], v156 offset:0x2000
	ds_read_b64_tr_b16 v[170:171], v156 offset:0x2800
	ds_read_b64_tr_b16 v[172:173], v156 offset:0x2200
	ds_read_b64_tr_b16 v[174:175], v156 offset:0x2a00
	ds_read_b64_tr_b16 v[180:181], v156 offset:0x2400
	ds_read_b64_tr_b16 v[182:183], v156 offset:0x2c00
	ds_read_b64_tr_b16 v[184:185], v156 offset:0x2600
	ds_read_b64_tr_b16 v[186:187], v156 offset:0x2e00
	global_load_dwordx4 v[74:77], v[74:75], off
	s_nop 0
	global_load_dwordx4 v[78:81], v[78:79], off
	v_addc_co_u32_e32 v165, vcc, 0, v151, vcc
	global_load_dwordx4 v[164:167], v[164:165], off
	s_waitcnt lgkmcnt(12)
	v_mfma_f32_32x32x16_bf16 v[18:33], v[130:133], v[230:233], v[18:33]
	v_exp_f32_e32 v220, v98
	v_exp_f32_e32 v177, v99
	v_exp_f32_e32 v193, v100
	s_waitcnt lgkmcnt(10)
	v_mfma_f32_32x32x16_bf16 v[34:49], v[130:133], v[234:237], v[34:49]
	v_exp_f32_e32 v195, v101
	v_exp_f32_e32 v197, v102
	v_exp_f32_e32 v199, v103
	s_waitcnt lgkmcnt(8)
	v_mfma_f32_32x32x16_bf16 v[50:65], v[130:133], v[242:245], v[50:65]
	v_exp_f32_e32 v201, v104
	v_exp_f32_e32 v203, v105
	v_cvt_pk_bf16_f32 v222, v220, v177
	v_cvt_pk_bf16_f32 v223, v193, v195
	s_waitcnt lgkmcnt(6)
	v_mfma_f32_32x32x16_bf16 v[2:17], v[66:69], v[168:171], v[2:17]
	ds_read_b64_tr_b16 v[188:189], v156 offset:0x3000
	ds_read_b64_tr_b16 v[190:191], v156 offset:0x3800
	ds_read_b64_tr_b16 v[230:231], v156 offset:0x3200
	ds_read_b64_tr_b16 v[232:233], v156 offset:0x3a00
	ds_read_b64_tr_b16 v[234:235], v156 offset:0x3400
	ds_read_b64_tr_b16 v[236:237], v156 offset:0x3c00
	ds_read_b64_tr_b16 v[242:243], v156 offset:0x3600
	ds_read_b64_tr_b16 v[244:245], v156 offset:0x3e00
	v_cvt_pk_bf16_f32 v224, v197, v199
	v_cvt_pk_bf16_f32 v225, v201, v203
	v_exp_f32_e32 v205, v106
	s_waitcnt lgkmcnt(12)
	v_mfma_f32_32x32x16_bf16 v[18:33], v[66:69], v[172:175], v[18:33]
	v_exp_f32_e32 v207, v107
	v_exp_f32_e32 v209, v108
	v_exp_f32_e32 v211, v109
	s_waitcnt lgkmcnt(10)
	v_mfma_f32_32x32x16_bf16 v[34:49], v[66:69], v[180:183], v[34:49]
	v_exp_f32_e32 v213, v110
	v_exp_f32_e32 v215, v111
	v_exp_f32_e32 v217, v112
	s_waitcnt lgkmcnt(8)
	v_mfma_f32_32x32x16_bf16 v[50:65], v[66:69], v[184:187], v[50:65]
	v_exp_f32_e32 v219, v113
	v_add_f32_e32 v139, 0, v220
	v_add_f32_e32 v238, v177, v139
	v_add_f32_e32 v238, v193, v238
	v_add_f32_e32 v238, v195, v238
	s_waitcnt lgkmcnt(6)
	v_mfma_f32_32x32x16_bf16 v[2:17], v[70:73], v[188:191], v[2:17]
	v_add_f32_e32 v238, v197, v238
	v_add_f32_e32 v238, v199, v238
	v_add_f32_e32 v238, v201, v238
	v_add_f32_e32 v238, v203, v238
	v_add_f32_e32 v238, v205, v238
	v_add_f32_e32 v238, v207, v238
	s_waitcnt lgkmcnt(4)
	v_mfma_f32_32x32x16_bf16 v[18:33], v[70:73], v[230:233], v[18:33]
	v_add_f32_e32 v238, v209, v238
	v_add_f32_e32 v238, v211, v238
	v_add_f32_e32 v238, v213, v238
	v_add_f32_e32 v238, v215, v238
	v_add_f32_e32 v238, v217, v238
	v_add_f32_e32 v238, v219, v238
	s_waitcnt lgkmcnt(2)
	v_mfma_f32_32x32x16_bf16 v[34:49], v[70:73], v[234:237], v[34:49]
	v_add_f32_e32 v238, v221, v238
	v_cvt_pk_bf16_f32 v226, v205, v207
	v_cvt_pk_bf16_f32 v227, v209, v211
	v_cvt_pk_bf16_f32 v228, v213, v215
	v_cvt_pk_bf16_f32 v229, v217, v219
	s_waitcnt lgkmcnt(0)
	v_mfma_f32_32x32x16_bf16 v[50:65], v[70:73], v[242:245], v[50:65]
	s_barrier
	s_waitcnt vmcnt(0)
	s_waitcnt vmcnt(2)
	ds_write_b128 v160, v[74:77]
	s_waitcnt vmcnt(1)
	ds_write_b128 v161, v[78:81]
	s_waitcnt vmcnt(0)
	ds_write_b128 v158, v[164:167] offset:32768
	s_waitcnt lgkmcnt(0)
	s_barrier
	ds_read_b128 v[66:69], v157 offset:32768
	ds_read_b128 v[70:73], v157 offset:36864
	ds_read_b128 v[164:167], v159 offset:32768
	ds_read_b128 v[172:175], v159 offset:36864
	ds_read_b128 v[230:233], v162 offset:32768
	ds_read_b128 v[234:237], v162 offset:36864
	ds_read_b128 v[168:171], v163 offset:32768
	ds_read_b128 v[242:245], v163 offset:36864
	v_exp_f32_e32 v176, v82
	v_exp_f32_e32 v192, v83
	v_exp_f32_e32 v194, v84
	v_exp_f32_e32 v196, v85
	s_waitcnt lgkmcnt(7)
	v_mfma_f32_32x32x16_bf16 v[98:113], v[66:69], v[126:129], 0
	v_exp_f32_e32 v198, v86
	v_add_f32_e32 v82, v176, v138
	s_waitcnt lgkmcnt(6)
	v_mfma_f32_32x32x16_bf16 v[66:81], v[70:73], v[126:129], 0
	v_exp_f32_e32 v200, v87
	v_add_f32_e32 v82, v192, v82
	v_exp_f32_e32 v202, v88
	v_add_f32_e32 v82, v194, v82
	s_waitcnt lgkmcnt(5)
	v_mfma_f32_32x32x16_bf16 v[98:113], v[164:167], v[122:125], v[98:113]
	v_exp_f32_e32 v204, v89
	v_add_f32_e32 v82, v196, v82
	v_exp_f32_e32 v206, v90
	s_waitcnt lgkmcnt(4)
	v_mfma_f32_32x32x16_bf16 v[66:81], v[172:175], v[122:125], v[66:81]
	ds_read_b64_tr_b16 v[180:181], v141 offset:0
	ds_read_b64_tr_b16 v[182:183], v141 offset:0x800
	ds_read_b64_tr_b16 v[164:165], v141 offset:0x200
	ds_read_b64_tr_b16 v[166:167], v141 offset:0xa00
	ds_read_b64_tr_b16 v[184:185], v141 offset:0x400
	ds_read_b64_tr_b16 v[186:187], v141 offset:0xc00
	ds_read_b64_tr_b16 v[188:189], v141 offset:0x600
	ds_read_b64_tr_b16 v[190:191], v141 offset:0xe00
	v_add_f32_e32 v82, v198, v82
	v_exp_f32_e32 v208, v91
	v_add_f32_e32 v82, v200, v82
	s_waitcnt lgkmcnt(11)
	v_mfma_f32_32x32x16_bf16 v[98:113], v[230:233], v[118:121], v[98:113]
	v_exp_f32_e32 v210, v92
	v_add_f32_e32 v82, v202, v82
	v_exp_f32_e32 v212, v93
	s_waitcnt lgkmcnt(10)
	v_mfma_f32_32x32x16_bf16 v[66:81], v[234:237], v[118:121], v[66:81]
	v_add_f32_e32 v82, v204, v82
	v_exp_f32_e32 v214, v94
	v_add_f32_e32 v82, v206, v82
	s_waitcnt lgkmcnt(9)
	v_mfma_f32_32x32x16_bf16 v[98:113], v[168:171], v[114:117], v[98:113]
	v_exp_f32_e32 v216, v95
	v_add_f32_e32 v82, v208, v82
	v_exp_f32_e32 v218, v96
	s_waitcnt lgkmcnt(8)
; #define SBAR() __builtin_amdgcn_sched_barrier(0)
; #define SWRITE(b, i) do { *(bf16x8*)(V_lds + (b) * SHM_V + vst0) = sr_[i].vs0; *(bf16x8*)(V_lds + (b) * SHM_V + vst1) = sr_[i].vs1; \
;     *(bf16x8*)(K_lds + (b) * SHM_K + kst) = sr_[i].ks0; } while (0)
; #define SWAIT() asm volatile("s_waitcnt vmcnt(0)" ::: "memory")
; #define SBAR() __builtin_amdgcn_sched_barrier(0)
; __device__ __forceinline__ void attn_unit(const bf16* __restrict__ Qb, const bf16* __restrict__ Kh, const bf16* __restrict__ Vh, bf16* __restrict__ Ob, int seq, char* lds) {
;     ...
;         pv_ks<1>(o, vb0 + SHM_V, pa1); pv_ks<2>(o, vb0 + SHM_V, pa2); pv_ks<3>(o, vb0 + SHM_V, pa3); SBAR();
;         softHalf(pA0, l_reg, pa0, pa1); SBAR();
;         __syncthreads(); SWAIT(); SWRITE(1, SO);
	v_mfma_f32_32x32x16_bf16 v[66:81], v[242:245], v[114:117], v[66:81]
	v_add_f32_e32 v82, v210, v82
	v_exp_f32_e32 v220, v97
	v_add_f32_e32 v82, v212, v82
	v_add_f32_e32 v82, v214, v82
	s_waitcnt lgkmcnt(6)
	v_mfma_f32_32x32x16_bf16 v[2:17], v[222:225], v[180:183], v[2:17]
	ds_read_b64_tr_b16 v[230:231], v141 offset:0x1000
	ds_read_b64_tr_b16 v[232:233], v141 offset:0x1800
	ds_read_b64_tr_b16 v[234:235], v141 offset:0x1200
	ds_read_b64_tr_b16 v[236:237], v141 offset:0x1a00
	ds_read_b64_tr_b16 v[168:169], v141 offset:0x1400
	ds_read_b64_tr_b16 v[170:171], v141 offset:0x1c00
	ds_read_b64_tr_b16 v[172:173], v141 offset:0x1600
	ds_read_b64_tr_b16 v[174:175], v141 offset:0x1e00
	v_add_f32_e32 v82, v216, v82
	v_add_f32_e32 v82, v218, v82
	v_add_f32_e32 v82, v220, v82
	v_add_f32_e32 v139, v82, v238
	s_waitcnt lgkmcnt(12)
	v_mfma_f32_32x32x16_bf16 v[18:33], v[222:225], v[164:167], v[18:33]
	v_cvt_pk_bf16_f32 v82, v176, v192
	v_cvt_pk_bf16_f32 v83, v194, v196
	v_cvt_pk_bf16_f32 v84, v198, v200
	v_cvt_pk_bf16_f32 v85, v202, v204
	s_waitcnt lgkmcnt(10)
	v_mfma_f32_32x32x16_bf16 v[34:49], v[222:225], v[184:187], v[34:49]
	v_cvt_pk_bf16_f32 v86, v206, v208
	v_cvt_pk_bf16_f32 v87, v210, v212
	v_cvt_pk_bf16_f32 v88, v214, v216
	v_cvt_pk_bf16_f32 v89, v218, v220
	s_waitcnt lgkmcnt(8)
	v_mfma_f32_32x32x16_bf16 v[50:65], v[222:225], v[188:191], v[50:65]
	v_add_co_u32_e32 v90, vcc, s43, v136
	s_nop 1
	v_addc_co_u32_e32 v91, vcc, 0, v137, vcc
	v_add_co_u32_e32 v94, vcc, s46, v136
	s_nop 1
	v_addc_co_u32_e32 v95, vcc, 0, v137, vcc
	v_add_co_u32_e32 v130, vcc, s47, v150
	global_load_dwordx4 v[90:93], v[90:91], off
	s_nop 0
	s_waitcnt lgkmcnt(6)
	v_mfma_f32_32x32x16_bf16 v[2:17], v[226:229], v[230:233], v[2:17]
	ds_read_b64_tr_b16 v[180:181], v141 offset:0x2000
	ds_read_b64_tr_b16 v[182:183], v141 offset:0x2800
	ds_read_b64_tr_b16 v[184:185], v141 offset:0x2200
	ds_read_b64_tr_b16 v[186:187], v141 offset:0x2a00
	ds_read_b64_tr_b16 v[188:189], v141 offset:0x2400
	ds_read_b64_tr_b16 v[190:191], v141 offset:0x2c00
	ds_read_b64_tr_b16 v[222:223], v141 offset:0x2600
	ds_read_b64_tr_b16 v[224:225], v141 offset:0x2e00
	global_load_dwordx4 v[94:97], v[94:95], off
	v_addc_co_u32_e32 v131, vcc, 0, v151, vcc
	global_load_dwordx4 v[164:167], v[130:131], off
	v_exp_f32_e32 v239, v98
	s_waitcnt lgkmcnt(12)
	v_mfma_f32_32x32x16_bf16 v[18:33], v[226:229], v[234:237], v[18:33]
	v_exp_f32_e32 v241, v99
	v_exp_f32_e32 v242, v100
	v_exp_f32_e32 v243, v101
	s_waitcnt lgkmcnt(10)
	v_mfma_f32_32x32x16_bf16 v[34:49], v[226:229], v[168:171], v[34:49]
	v_exp_f32_e32 v244, v102
	v_exp_f32_e32 v98, v106
	v_add_f32_e32 v106, 0, v239
	s_waitcnt lgkmcnt(8)
	v_mfma_f32_32x32x16_bf16 v[50:65], v[226:229], v[172:175], v[50:65]
	v_exp_f32_e32 v245, v103
	v_add_f32_e32 v106, v241, v106
	v_exp_f32_e32 v246, v104
	v_add_f32_e32 v106, v242, v106
	s_waitcnt lgkmcnt(6)
	v_mfma_f32_32x32x16_bf16 v[2:17], v[82:85], v[180:183], v[2:17]
	ds_read_b64_tr_b16 v[230:231], v141 offset:0x3000
	ds_read_b64_tr_b16 v[232:233], v141 offset:0x3800
	ds_read_b64_tr_b16 v[234:235], v141 offset:0x3200
	ds_read_b64_tr_b16 v[236:237], v141 offset:0x3a00
	ds_read_b64_tr_b16 v[168:169], v141 offset:0x3400
	ds_read_b64_tr_b16 v[170:171], v141 offset:0x3c00
	ds_read_b64_tr_b16 v[172:173], v141 offset:0x3600
	ds_read_b64_tr_b16 v[174:175], v141 offset:0x3e00
	v_exp_f32_e32 v247, v105
	v_add_f32_e32 v106, v243, v106
	v_add_f32_e32 v106, v244, v106
	v_exp_f32_e32 v99, v107
	s_waitcnt lgkmcnt(12)
	v_mfma_f32_32x32x16_bf16 v[18:33], v[82:85], v[184:187], v[18:33]
	v_add_f32_e32 v106, v245, v106
	v_exp_f32_e32 v100, v108
	v_add_f32_e32 v106, v246, v106
	v_exp_f32_e32 v101, v109
	s_waitcnt lgkmcnt(10)
	v_mfma_f32_32x32x16_bf16 v[34:49], v[82:85], v[188:191], v[34:49]
	v_add_f32_e32 v106, v247, v106
	v_exp_f32_e32 v102, v110
	v_add_f32_e32 v106, v98, v106
	v_exp_f32_e32 v103, v111
	s_waitcnt lgkmcnt(8)
	v_mfma_f32_32x32x16_bf16 v[50:65], v[82:85], v[222:225], v[50:65]
	v_add_f32_e32 v106, v99, v106
	v_exp_f32_e32 v104, v112
	v_add_f32_e32 v106, v100, v106
	s_waitcnt lgkmcnt(6)
	v_mfma_f32_32x32x16_bf16 v[2:17], v[86:89], v[230:233], v[2:17]
	v_exp_f32_e32 v105, v113
	v_add_f32_e32 v106, v101, v106
	v_add_f32_e32 v106, v102, v106
	v_add_f32_e32 v106, v103, v106
	v_add_f32_e32 v106, v104, v106
	v_add_f32_e32 v106, v105, v106
	s_waitcnt lgkmcnt(4)
	v_mfma_f32_32x32x16_bf16 v[18:33], v[86:89], v[234:237], v[18:33]
	v_cvt_pk_bf16_f32 v134, v239, v241
	v_cvt_pk_bf16_f32 v135, v242, v243
	v_cvt_pk_bf16_f32 v136, v244, v245
	v_cvt_pk_bf16_f32 v137, v246, v247
	s_waitcnt lgkmcnt(2)
	v_mfma_f32_32x32x16_bf16 v[34:49], v[86:89], v[168:171], v[34:49]
	v_cvt_pk_bf16_f32 v130, v98, v99
	v_cvt_pk_bf16_f32 v131, v100, v101
	v_cvt_pk_bf16_f32 v132, v102, v103
	v_cvt_pk_bf16_f32 v133, v104, v105
	v_add_f32_e32 v139, v139, v106
	s_waitcnt lgkmcnt(0)
	v_mfma_f32_32x32x16_bf16 v[50:65], v[86:89], v[172:175], v[50:65]
	s_barrier
	s_waitcnt vmcnt(0)
	s_add_i32 s10, s10, 2
	v_lshl_add_u64 v[146:147], v[146:147], 0, s[0:1]
	s_cmp_gt_u32 s10, 32
	v_lshl_add_u64 v[148:149], v[148:149], 0, s[4:5]
	s_waitcnt vmcnt(2)
	ds_write_b128 v160, v[90:93] offset:16384
	s_waitcnt vmcnt(1)
	ds_write_b128 v161, v[94:97] offset:16384
	s_waitcnt vmcnt(0)
	ds_write_b128 v158, v[164:167] offset:40960
	s_waitcnt lgkmcnt(0)
	s_barrier
	s_cbranch_scc0 .LBB0_531
; #define SBAR() __builtin_amdgcn_sched_barrier(0)
; #define SBAR() __builtin_amdgcn_sched_barrier(0)
; __device__ __forceinline__ void attn_unit(const bf16* __restrict__ Qb, const bf16* __restrict__ Kh, const bf16* __restrict__ Vh, bf16* __restrict__ Ob, int seq, char* lds) {
;     ...
;     SBAR(); qkt(pB0, pB1, K_lds + SHM_K, qr, r32, hi); pv_ks<0>(o, vb0, pa0); SBAR();
;     softHalf(pA1, l_reg, pa2, pa3); SBAR();
;     pv_ks<1>(o, vb0, pa1); pv_ks<2>(o, vb0, pa2); pv_ks<3>(o, vb0, pa3); SBAR();
	v_and_b32_e32 v82, 0x3fffffc0, v143
	v_lshl_add_u32 v143, v82, 2, 0
	ds_read_b128 v[82:85], v157 offset:40960
	ds_read_b128 v[86:89], v157 offset:45056
	s_waitcnt lgkmcnt(1)
	v_mfma_f32_32x32x16_bf16 v[98:113], v[82:85], v[126:129], 0
	s_waitcnt lgkmcnt(0)
	v_mfma_f32_32x32x16_bf16 v[82:97], v[86:89], v[126:129], 0
	ds_read_b128 v[126:129], v159 offset:40960
	ds_read_b128 v[146:149], v159 offset:45056
	s_waitcnt lgkmcnt(1)
	v_mfma_f32_32x32x16_bf16 v[98:113], v[126:129], v[122:125], v[98:113]
	s_waitcnt lgkmcnt(0)
	v_mfma_f32_32x32x16_bf16 v[82:97], v[146:149], v[122:125], v[82:97]
	ds_read_b128 v[122:125], v162 offset:40960
	ds_read_b128 v[126:129], v162 offset:45056
	s_waitcnt lgkmcnt(1)
	v_mfma_f32_32x32x16_bf16 v[98:113], v[122:125], v[118:121], v[98:113]
	s_waitcnt lgkmcnt(0)
	v_mfma_f32_32x32x16_bf16 v[82:97], v[126:129], v[118:121], v[82:97]
	ds_read_b128 v[118:121], v163 offset:40960
	ds_read_b128 v[122:125], v163 offset:45056
	ds_read_b64_tr_b16 v[126:127], v156 offset:0
	ds_read_b64_tr_b16 v[128:129], v156 offset:0x800
	s_waitcnt lgkmcnt(1)
	v_mfma_f32_32x32x16_bf16 v[98:113], v[118:121], v[114:117], v[98:113]
	ds_read_b64_tr_b16 v[118:119], v156 offset:0x200
	ds_read_b64_tr_b16 v[120:121], v156 offset:0xa00
	ds_read_b64_tr_b16 v[146:147], v156 offset:0x400
	ds_read_b64_tr_b16 v[148:149], v156 offset:0xc00
	ds_read_b64_tr_b16 v[158:159], v156 offset:0x600
	ds_read_b64_tr_b16 v[160:161], v156 offset:0xe00
	s_waitcnt lgkmcnt(0)
	s_waitcnt lgkmcnt(0)
	v_mfma_f32_32x32x16_bf16 v[82:97], v[122:125], v[114:117], v[82:97]
	v_mfma_f32_32x32x16_bf16 v[2:17], v[134:137], v[126:129], v[2:17]
	v_mfma_f32_32x32x16_bf16 v[18:33], v[134:137], v[118:121], v[18:33]
	v_mfma_f32_32x32x16_bf16 v[34:49], v[134:137], v[146:149], v[34:49]
	v_mfma_f32_32x32x16_bf16 v[50:65], v[134:137], v[158:161], v[50:65]
	v_exp_f32_e32 v66, v66
	v_exp_f32_e32 v67, v67
	v_exp_f32_e32 v68, v68
	v_exp_f32_e32 v69, v69
	v_exp_f32_e32 v70, v70
	v_add_f32_e32 v114, 0, v66
	v_exp_f32_e32 v71, v71
	v_add_f32_e32 v114, v67, v114
	v_exp_f32_e32 v72, v72
	v_add_f32_e32 v114, v68, v114
	v_exp_f32_e32 v73, v73
	v_add_f32_e32 v114, v69, v114
	v_exp_f32_e32 v74, v74
	v_add_f32_e32 v114, v70, v114
	v_exp_f32_e32 v75, v75
	v_add_f32_e32 v114, v71, v114
	v_exp_f32_e32 v76, v76
	v_add_f32_e32 v114, v72, v114
	v_exp_f32_e32 v77, v77
	v_add_f32_e32 v114, v73, v114
	v_exp_f32_e32 v78, v78
	v_add_f32_e32 v114, v74, v114
	v_exp_f32_e32 v79, v79
	v_add_f32_e32 v114, v75, v114
	v_exp_f32_e32 v80, v80
	v_add_f32_e32 v114, v76, v114
	v_exp_f32_e32 v81, v81
	v_add_f32_e32 v114, v77, v114
	v_add_f32_e32 v114, v78, v114
	v_add_f32_e32 v114, v79, v114
	v_add_f32_e32 v114, v80, v114
	v_cvt_pk_bf16_f32 v66, v66, v67
	v_cvt_pk_bf16_f32 v67, v68, v69
	v_cvt_pk_bf16_f32 v68, v70, v71
	v_cvt_pk_bf16_f32 v69, v72, v73
	v_add_f32_e32 v114, v81, v114
	v_cvt_pk_bf16_f32 v70, v74, v75
	v_cvt_pk_bf16_f32 v71, v76, v77
	v_cvt_pk_bf16_f32 v72, v78, v79
	v_cvt_pk_bf16_f32 v73, v80, v81
	v_add_f32_e32 v126, v139, v114
	ds_read_b64_tr_b16 v[74:75], v156 offset:0x1000
	ds_read_b64_tr_b16 v[76:77], v156 offset:0x1800
	ds_read_b64_tr_b16 v[78:79], v156 offset:0x1200
	ds_read_b64_tr_b16 v[80:81], v156 offset:0x1a00
	ds_read_b64_tr_b16 v[114:115], v156 offset:0x1400
	ds_read_b64_tr_b16 v[116:117], v156 offset:0x1c00
	ds_read_b64_tr_b16 v[118:119], v156 offset:0x1600
	ds_read_b64_tr_b16 v[120:121], v156 offset:0x1e00
	s_waitcnt lgkmcnt(0)
	s_nop 0
	v_mfma_f32_32x32x16_bf16 v[2:17], v[130:133], v[74:77], v[2:17]
	ds_read_b64_tr_b16 v[74:75], v156 offset:0x2000
	ds_read_b64_tr_b16 v[76:77], v156 offset:0x2800
	v_mfma_f32_32x32x16_bf16 v[18:33], v[130:133], v[78:81], v[18:33]
	ds_read_b64_tr_b16 v[78:79], v156 offset:0x2200
	ds_read_b64_tr_b16 v[80:81], v156 offset:0x2a00
	v_mfma_f32_32x32x16_bf16 v[34:49], v[130:133], v[114:117], v[34:49]
	ds_read_b64_tr_b16 v[114:115], v156 offset:0x2400
	ds_read_b64_tr_b16 v[116:117], v156 offset:0x2c00
	ds_read_b64_tr_b16 v[122:123], v156 offset:0x2600
	ds_read_b64_tr_b16 v[124:125], v156 offset:0x2e00
	s_waitcnt lgkmcnt(0)
	v_mfma_f32_32x32x16_bf16 v[50:65], v[130:133], v[118:121], v[50:65]
	v_mfma_f32_32x32x16_bf16 v[2:17], v[66:69], v[74:77], v[2:17]
	ds_read_b64_tr_b16 v[74:75], v156 offset:0x3000
	ds_read_b64_tr_b16 v[76:77], v156 offset:0x3800
	v_mfma_f32_32x32x16_bf16 v[18:33], v[66:69], v[78:81], v[18:33]
	ds_read_b64_tr_b16 v[78:79], v156 offset:0x3200
	ds_read_b64_tr_b16 v[80:81], v156 offset:0x3a00
	v_mfma_f32_32x32x16_bf16 v[34:49], v[66:69], v[114:117], v[34:49]
	ds_read_b64_tr_b16 v[114:115], v156 offset:0x3400
	ds_read_b64_tr_b16 v[116:117], v156 offset:0x3c00
	ds_read_b64_tr_b16 v[118:119], v156 offset:0x3600
	ds_read_b64_tr_b16 v[120:121], v156 offset:0x3e00
	s_waitcnt lgkmcnt(0)
; #define SBAR() __builtin_amdgcn_sched_barrier(0)
; #define SBAR() __builtin_amdgcn_sched_barrier(0)
; __device__ __forceinline__ void attn_unit(const bf16* __restrict__ Qb, const bf16* __restrict__ Kh, const bf16* __restrict__ Vh, bf16* __restrict__ Ob, int seq, char* lds) {
;     ...
;     pv_ks<1>(o, vb0, pa1); pv_ks<2>(o, vb0, pa2); pv_ks<3>(o, vb0, pa3); SBAR();
;     softHalf(pB0, l_reg, pa0, pa1); SBAR();
;     pv_ks<0>(o, vb0 + SHM_V, pa0); SBAR();
;     softHalf(pB1, l_reg, pa2, pa3); SBAR();
;     pv_ks<1>(o, vb0 + SHM_V, pa1); pv_ks<2>(o, vb0 + SHM_V, pa2); pv_ks<3>(o, vb0 + SHM_V, pa3);
;     { auto rr = __builtin_amdgcn_permlane32_swap(__float_as_uint(l_reg), __float_as_uint(l_reg), false, false); l_reg = __uint_as_float(rr[0]) + __uint_as_float(rr[1]); }
;     if (hi == 0) wsf[r32] = l_reg; asm volatile("s_waitcnt lgkmcnt(0)" ::: "memory");
	v_mfma_f32_32x32x16_bf16 v[50:65], v[66:69], v[122:125], v[50:65]
	v_mfma_f32_32x32x16_bf16 v[2:17], v[70:73], v[74:77], v[2:17]
	v_mfma_f32_32x32x16_bf16 v[18:33], v[70:73], v[78:81], v[18:33]
	v_mfma_f32_32x32x16_bf16 v[34:49], v[70:73], v[114:117], v[34:49]
	v_mfma_f32_32x32x16_bf16 v[50:65], v[70:73], v[118:121], v[50:65]
	v_exp_f32_e32 v66, v98
	v_exp_f32_e32 v67, v99
	v_exp_f32_e32 v68, v100
	v_exp_f32_e32 v69, v101
	v_exp_f32_e32 v70, v102
	v_add_f32_e32 v98, 0, v66
	v_exp_f32_e32 v71, v103
	v_add_f32_e32 v98, v67, v98
	v_exp_f32_e32 v72, v104
	v_add_f32_e32 v98, v68, v98
	v_exp_f32_e32 v73, v105
	v_add_f32_e32 v98, v69, v98
	v_exp_f32_e32 v74, v106
	v_add_f32_e32 v98, v70, v98
	v_exp_f32_e32 v75, v107
	v_add_f32_e32 v98, v71, v98
	v_exp_f32_e32 v76, v108
	v_add_f32_e32 v98, v72, v98
	v_exp_f32_e32 v77, v109
	v_add_f32_e32 v98, v73, v98
	v_exp_f32_e32 v78, v110
	v_add_f32_e32 v98, v74, v98
	v_exp_f32_e32 v79, v111
	v_add_f32_e32 v98, v75, v98
	v_exp_f32_e32 v80, v112
	v_add_f32_e32 v98, v76, v98
	v_exp_f32_e32 v81, v113
	v_add_f32_e32 v98, v77, v98
	v_add_f32_e32 v98, v78, v98
	v_add_f32_e32 v98, v79, v98
	v_add_f32_e32 v98, v80, v98
	v_cvt_pk_bf16_f32 v66, v66, v67
	v_cvt_pk_bf16_f32 v67, v68, v69
	v_cvt_pk_bf16_f32 v68, v70, v71
	v_cvt_pk_bf16_f32 v69, v72, v73
	v_add_f32_e32 v98, v81, v98
	v_cvt_pk_bf16_f32 v70, v74, v75
	v_cvt_pk_bf16_f32 v71, v76, v77
	v_cvt_pk_bf16_f32 v72, v78, v79
	v_cvt_pk_bf16_f32 v73, v80, v81
	v_add_f32_e32 v106, v126, v98
	ds_read_b64_tr_b16 v[74:75], v141 offset:0
	ds_read_b64_tr_b16 v[76:77], v141 offset:0x800
	ds_read_b64_tr_b16 v[78:79], v141 offset:0x200
	ds_read_b64_tr_b16 v[80:81], v141 offset:0xa00
	ds_read_b64_tr_b16 v[98:99], v141 offset:0x400
	ds_read_b64_tr_b16 v[100:101], v141 offset:0xc00
	ds_read_b64_tr_b16 v[102:103], v141 offset:0x600
	ds_read_b64_tr_b16 v[104:105], v141 offset:0xe00
	s_waitcnt lgkmcnt(0)
	s_nop 0
	v_mfma_f32_32x32x16_bf16 v[2:17], v[66:69], v[74:77], v[2:17]
	v_mfma_f32_32x32x16_bf16 v[18:33], v[66:69], v[78:81], v[18:33]
	v_mfma_f32_32x32x16_bf16 v[34:49], v[66:69], v[98:101], v[34:49]
	v_mfma_f32_32x32x16_bf16 v[50:65], v[66:69], v[102:105], v[50:65]
	v_exp_f32_e32 v67, v82
	v_exp_f32_e32 v68, v83
	v_exp_f32_e32 v69, v84
	v_exp_f32_e32 v75, v85
	v_exp_f32_e32 v76, v86
	v_add_f32_e32 v66, 0, v67
	v_exp_f32_e32 v77, v87
	v_add_f32_e32 v66, v68, v66
	v_exp_f32_e32 v78, v88
	v_add_f32_e32 v66, v69, v66
	v_exp_f32_e32 v79, v89
	v_add_f32_e32 v66, v75, v66
	v_exp_f32_e32 v80, v90
	v_add_f32_e32 v66, v76, v66
	v_exp_f32_e32 v81, v91
	v_add_f32_e32 v66, v77, v66
	v_exp_f32_e32 v82, v92
	v_add_f32_e32 v66, v78, v66
	v_exp_f32_e32 v83, v93
	v_add_f32_e32 v66, v79, v66
	v_exp_f32_e32 v84, v94
	v_add_f32_e32 v66, v80, v66
	v_exp_f32_e32 v85, v95
	v_add_f32_e32 v66, v81, v66
	v_exp_f32_e32 v86, v96
	v_add_f32_e32 v66, v82, v66
	v_exp_f32_e32 v87, v97
	v_add_f32_e32 v66, v83, v66
	v_add_f32_e32 v66, v84, v66
	v_add_f32_e32 v66, v85, v66
	v_add_f32_e32 v66, v86, v66
	v_add_f32_e32 v66, v87, v66
	v_add_f32_e32 v66, v66, v106
	v_cvt_pk_bf16_f32 v74, v67, v68
	v_cvt_pk_bf16_f32 v75, v69, v75
	v_cvt_pk_bf16_f32 v76, v76, v77
	v_cvt_pk_bf16_f32 v77, v78, v79
	v_cvt_pk_bf16_f32 v78, v80, v81
	v_cvt_pk_bf16_f32 v79, v82, v83
	v_cvt_pk_bf16_f32 v80, v84, v85
	v_cvt_pk_bf16_f32 v81, v86, v87
	s_nop 0
	ds_read_b64_tr_b16 v[82:83], v141 offset:0x1000
	ds_read_b64_tr_b16 v[84:85], v141 offset:0x1800
	ds_read_b64_tr_b16 v[86:87], v141 offset:0x1200
	ds_read_b64_tr_b16 v[88:89], v141 offset:0x1a00
	ds_read_b64_tr_b16 v[90:91], v141 offset:0x1400
	ds_read_b64_tr_b16 v[92:93], v141 offset:0x1c00
	ds_read_b64_tr_b16 v[94:95], v141 offset:0x1600
	ds_read_b64_tr_b16 v[96:97], v141 offset:0x1e00
	s_waitcnt lgkmcnt(0)
	s_nop 0
	v_mfma_f32_32x32x16_bf16 v[2:17], v[70:73], v[82:85], v[2:17]
	ds_read_b64_tr_b16 v[82:83], v141 offset:0x2000
	ds_read_b64_tr_b16 v[84:85], v141 offset:0x2800
	v_mfma_f32_32x32x16_bf16 v[18:33], v[70:73], v[86:89], v[18:33]
	ds_read_b64_tr_b16 v[86:87], v141 offset:0x2200
	ds_read_b64_tr_b16 v[88:89], v141 offset:0x2a00
	v_mfma_f32_32x32x16_bf16 v[34:49], v[70:73], v[90:93], v[34:49]
	ds_read_b64_tr_b16 v[90:91], v141 offset:0x2400
	ds_read_b64_tr_b16 v[92:93], v141 offset:0x2c00
	ds_read_b64_tr_b16 v[98:99], v141 offset:0x2600
	ds_read_b64_tr_b16 v[100:101], v141 offset:0x2e00
	s_waitcnt lgkmcnt(0)
	v_mfma_f32_32x32x16_bf16 v[50:65], v[70:73], v[94:97], v[50:65]
	ds_read_b64_tr_b16 v[68:69], v141 offset:0x3000
	ds_read_b64_tr_b16 v[70:71], v141 offset:0x3800
	v_mfma_f32_32x32x16_bf16 v[2:17], v[74:77], v[82:85], v[2:17]
	ds_read_b64_tr_b16 v[82:83], v141 offset:0x3200
	ds_read_b64_tr_b16 v[84:85], v141 offset:0x3a00
	v_mfma_f32_32x32x16_bf16 v[18:33], v[74:77], v[86:89], v[18:33]
	ds_read_b64_tr_b16 v[86:87], v141 offset:0x3400
	ds_read_b64_tr_b16 v[88:89], v141 offset:0x3c00
	v_mfma_f32_32x32x16_bf16 v[34:49], v[74:77], v[90:93], v[34:49]
	ds_read_b64_tr_b16 v[90:91], v141 offset:0x3600
	ds_read_b64_tr_b16 v[92:93], v141 offset:0x3e00
	s_waitcnt lgkmcnt(0)
	v_mfma_f32_32x32x16_bf16 v[50:65], v[74:77], v[98:101], v[50:65]
	v_mfma_f32_32x32x16_bf16 v[2:17], v[78:81], v[68:71], v[2:17]
	v_mov_b32_e32 v67, v66
	s_nop 1
	v_permlane32_swap_b32_e32 v66, v67
	v_cmp_gt_u32_e32 vcc, 32, v145
	v_mfma_f32_32x32x16_bf16 v[18:33], v[78:81], v[82:85], v[18:33]
	v_mfma_f32_32x32x16_bf16 v[34:49], v[78:81], v[86:89], v[34:49]
	v_mfma_f32_32x32x16_bf16 v[50:65], v[78:81], v[90:93], v[50:65]
	s_and_saveexec_b64 s[10:11], vcc
	s_cbranch_execz .LBB0_529
	v_add_f32_e32 v66, v66, v67
	v_lshl_add_u32 v67, v153, 2, v143
	ds_write_b32 v67, v66 offset:49152
	s_branch .LBB0_529
